# one static s_setprio 1 for waves 4-7 during the attention phase
# baseline (speedup 1.0000x reference)
; #define LAS __attribute__((address_space(3)))
; __global__ void __launch_bounds__(NWAVES * 64, 2) fwd_megakernel(Args args) {
;     ...
;         LAS unsigned char* wl = lds + wave * 16384;
;         if (NGW == 2048) {
;             const int c0 = 65 * (bx & 7), wx = (bx >> 3) * NWAVES + wave;
; #pragma unroll 1
;             for (int k = 0; k < 3; ++k) { const int j = wx + 256 * k; if (j < 520) attn_item<false>(U, sink_win, c0 + (j >> 3), j & 7, wl, tbl, lane); }
;             if (wx >= 8) { const int w2 = wx - 8;
; #pragma unroll 1
;                 for (int k = 0; k < 3; ++k) { const int j = w2 + 248 * k; if (k < 2 || w2 < 24) attn_item<true>(U, sink_win, c0 + (j >> 3), j & 7, wl, tbl, lane); } }
.LBB0_597:
	s_andn2_b64 vcc, exec, s[0:1]
	s_cbranch_vccnz .LBB0_662
	s_cmp_lt_u32 s25, 4
	s_cbranch_scc1 .Lprio_p2
	s_setprio 1
.Lprio_p2:
	s_bfe_u32 s12, s13, 0x30006
	s_and_b32 s0, s94, -8
	s_lshl_b32 s15, s12, 6
	s_and_b32 s24, s94, 7
	s_add_i32 s3, s25, s0
	s_add_i32 s2, s15, 0x700
	s_add_i32 s13, s15, 0x15700
	s_add_i32 s14, s15, 0x900
	s_add_i32 s15, s15, 0x15900
	s_lshl_b32 s0, s12, 7
	s_add_u32 s0, s82, s0
	s_mul_i32 s4, s12, 0x404
	s_addc_u32 s1, s83, 0
	s_add_i32 s17, s4, 0
	s_mulk_i32 s24, 0x41
	s_mov_b32 s16, 0
	s_add_i32 s17, s17, 0x20200
	s_movk_i32 s18, 0x1500
	s_movk_i32 s19, 0x2a00
	v_mov_b32_e32 v147, 0
	s_add_i32 s23, s22, 0x400
	s_add_i32 s25, s22, 0x800
	s_add_i32 s26, s22, 0xc00
	s_movk_i32 s20, 0x1000
	s_add_i32 s27, s22, 0x1000
	s_add_i32 s28, s22, 0x1400
	s_add_i32 s29, s22, 0x1800
	s_add_i32 s30, s22, 0x1c00
	s_add_i32 s31, s22, 0x2000
	s_add_i32 s34, s22, 0x2400
	s_add_i32 s35, s22, 0x2800
	s_add_i32 s46, s22, 0x2c00
	s_add_i32 s47, s22, 0x3000
	s_add_i32 s90, s22, 0x3400
	s_add_i32 s91, s22, 0x3800
	s_add_i32 s92, s22, 0x3c00
	v_mbcnt_hi_u32_b32 v227, -1, v225
	s_branch .LBB0_601

; __device__ __forceinline__ unsigned xb_add(unsigned* p, unsigned v) { return __hip_atomic_fetch_add(p, v, __ATOMIC_RELAXED, __HIP_MEMORY_SCOPE_AGENT); }
; __device__ __forceinline__ void xcd_barrier(const XcdBarrier& b) {
;     asm volatile("s_waitcnt vmcnt(0)" ::: "memory");
;     __syncthreads();
;     if (threadIdx.x == 0) {
;         unsigned* bar = b.bar;
;         __builtin_amdgcn_s_waitcnt(0);
;         unsigned nloc = b.st[0], nx = b.st[1];
;         if (nloc == 0u) { xcd_barrier_complete(bar, b.x, nloc, nx); b.st[0] = nloc; b.st[1] = nx; }
;         const unsigned old = xb_add(&bar[XB_XSUB(b.x)], 1u);
; __global__ void __launch_bounds__(NWAVES * 64, 2) fwd_megakernel(Args args) {
;     ...
;         __syncthreads();
;     }
;     xcd_barrier(xbar);
.LBB0_662:
	s_setprio 0
	s_waitcnt vmcnt(0)
	s_barrier
	s_waitcnt vmcnt(0)
	s_barrier
	s_and_saveexec_b64 s[0:1], s[54:55]
	v_readlane_b32 s20, v254, 4
	v_readlane_b32 s21, v254, 5
	s_cbranch_execz .LBB0_710
	s_add_i32 s2, 0, 0x20020
	v_mov_b32_e32 v1, s2
	s_waitcnt vmcnt(0) expcnt(0) lgkmcnt(0)
	ds_read_b32 v3, v1
	s_add_i32 s2, 0, 0x20024
	v_mov_b32_e32 v1, s2
	ds_read_b32 v1, v1
	s_waitcnt lgkmcnt(1)
	v_cmp_ne_u32_e32 vcc, 0, v3
	s_cbranch_vccnz .LBB0_678
	v_readlane_b32 s2, v254, 0
	v_readlane_b32 s3, v254, 1
	s_load_dwordx2 s[4:5], s[2:3], 0x4
	s_mov_b32 s2, 1
	v_mov_b32_e32 v17, 0
	s_waitcnt lgkmcnt(0)
	s_mul_i32 s3, s4, s93
	s_mul_i32 s3, s3, s5
	s_branch .LBB0_666
